# attention and pool mixer item-loop heads aligned to 64 bytes
# baseline (speedup 1.0000x reference)
.LBB0_43:
	v_sub_f32_e32 v0, v157, v156
	v_exp_f32_e32 v0, v0
	v_add_f32_e32 v1, v158, v159
	s_lshl_b32 s6, s40, 4
	s_and_b32 s6, s6, 0xfffff800
	v_add_f32_e32 v0, v0, v1
	v_div_scale_f32 v1, s[8:9], v0, v0, 1.0
	v_rcp_f32_e32 v2, v1
	s_lshl_b32 s7, s39, 6
	s_or_b32 s6, s7, s6
	s_lshl_b32 s90, s28, 9
	v_fma_f32 v3, -v1, v2, 1.0
	v_fmac_f32_e32 v2, v3, v2
	v_div_scale_f32 v3, vcc, 1.0, v0, 1.0
	v_mul_f32_e32 v4, v3, v2
	v_fma_f32 v5, -v1, v4, v3
	v_fmac_f32_e32 v4, v5, v2
	v_fma_f32 v1, -v1, v4, v3
	v_div_fmas_f32 v1, v1, v2, v4
	v_div_fixup_f32 v8, v1, v0, 1.0
	ds_read2_b64 v[0:3], v205 offset1:2
	ds_read2_b64 v[4:7], v205 offset0:4 offset1:6
	v_pk_mul_f32 v[10:11], v[8:9], v[80:81] op_sel_hi:[0,1]
	s_sub_i32 s37, s37, s25
	s_and_b64 vcc, exec, s[26:27]
	s_waitcnt lgkmcnt(1)
	v_lshlrev_b32_e32 v12, 16, v0
	v_and_b32_e32 v13, 0xffff0000, v0
	v_pk_mul_f32 v[10:11], v[10:11], v[12:13]
	v_lshlrev_b32_e32 v12, 16, v1
	v_cvt_pk_bf16_f32 v0, v10, v11
	v_pk_mul_f32 v[10:11], v[8:9], v[82:83] op_sel_hi:[0,1]
	v_and_b32_e32 v13, 0xffff0000, v1
	v_pk_mul_f32 v[10:11], v[10:11], v[12:13]
	v_lshlrev_b32_e32 v12, 16, v2
	v_cvt_pk_bf16_f32 v1, v10, v11
	v_pk_mul_f32 v[10:11], v[8:9], v[84:85] op_sel_hi:[0,1]
	v_and_b32_e32 v13, 0xffff0000, v2
	v_pk_mul_f32 v[10:11], v[10:11], v[12:13]
	v_lshlrev_b32_e32 v12, 16, v3
	v_cvt_pk_bf16_f32 v2, v10, v11
	v_pk_mul_f32 v[10:11], v[8:9], v[86:87] op_sel_hi:[0,1]
	v_and_b32_e32 v13, 0xffff0000, v3
	v_pk_mul_f32 v[10:11], v[10:11], v[12:13]
	s_nop 0
	v_cvt_pk_bf16_f32 v3, v10, v11
	ds_write2_b64 v205, v[0:1], v[2:3] offset1:2
	v_pk_mul_f32 v[0:1], v[8:9], v[88:89] op_sel_hi:[0,1]
	s_waitcnt lgkmcnt(1)
	v_lshlrev_b32_e32 v2, 16, v4
	v_and_b32_e32 v3, 0xffff0000, v4
	v_pk_mul_f32 v[0:1], v[0:1], v[2:3]
	v_pk_mul_f32 v[2:3], v[8:9], v[90:91] op_sel_hi:[0,1]
	v_lshlrev_b32_e32 v4, 16, v5
	v_and_b32_e32 v5, 0xffff0000, v5
	v_pk_mul_f32 v[2:3], v[2:3], v[4:5]
	v_cvt_pk_bf16_f32 v0, v0, v1
	v_cvt_pk_bf16_f32 v1, v2, v3
	v_pk_mul_f32 v[2:3], v[8:9], v[92:93] op_sel_hi:[0,1]
	v_lshlrev_b32_e32 v4, 16, v6
	v_and_b32_e32 v5, 0xffff0000, v6
	v_pk_mul_f32 v[2:3], v[2:3], v[4:5]
	v_pk_mul_f32 v[4:5], v[8:9], v[94:95] op_sel_hi:[0,1]
	v_lshlrev_b32_e32 v6, 16, v7
	v_and_b32_e32 v7, 0xffff0000, v7
	v_pk_mul_f32 v[4:5], v[4:5], v[6:7]
	v_cvt_pk_bf16_f32 v2, v2, v3
	v_cvt_pk_bf16_f32 v3, v4, v5
	ds_write2_b64 v205, v[0:1], v[2:3] offset0:4 offset1:6
	ds_read2_b64 v[0:3], v205 offset0:8 offset1:10
	v_pk_mul_f32 v[4:5], v[8:9], v[64:65] op_sel_hi:[0,1]
	s_waitcnt lgkmcnt(0)
	v_lshlrev_b32_e32 v6, 16, v0
	v_and_b32_e32 v7, 0xffff0000, v0
	v_pk_mul_f32 v[4:5], v[4:5], v[6:7]
	v_lshlrev_b32_e32 v6, 16, v1
	v_cvt_pk_bf16_f32 v0, v4, v5
	v_pk_mul_f32 v[4:5], v[8:9], v[66:67] op_sel_hi:[0,1]
	v_and_b32_e32 v7, 0xffff0000, v1
	v_pk_mul_f32 v[4:5], v[4:5], v[6:7]
	v_lshlrev_b32_e32 v6, 16, v2
	v_cvt_pk_bf16_f32 v1, v4, v5
	v_pk_mul_f32 v[4:5], v[8:9], v[68:69] op_sel_hi:[0,1]
	v_and_b32_e32 v7, 0xffff0000, v2
	v_pk_mul_f32 v[4:5], v[4:5], v[6:7]
	v_lshlrev_b32_e32 v6, 16, v3
	v_cvt_pk_bf16_f32 v2, v4, v5
	v_pk_mul_f32 v[4:5], v[8:9], v[70:71] op_sel_hi:[0,1]
	v_and_b32_e32 v7, 0xffff0000, v3
	v_pk_mul_f32 v[4:5], v[4:5], v[6:7]
	s_nop 0
	v_cvt_pk_bf16_f32 v3, v4, v5
	ds_write2_b64 v205, v[0:1], v[2:3] offset0:8 offset1:10
	ds_read2_b64 v[0:3], v205 offset0:12 offset1:14
	v_pk_mul_f32 v[4:5], v[8:9], v[72:73] op_sel_hi:[0,1]
	s_waitcnt lgkmcnt(0)
	v_lshlrev_b32_e32 v6, 16, v0
	v_and_b32_e32 v7, 0xffff0000, v0
	v_pk_mul_f32 v[4:5], v[4:5], v[6:7]
	v_lshlrev_b32_e32 v6, 16, v1
	v_cvt_pk_bf16_f32 v0, v4, v5
	v_pk_mul_f32 v[4:5], v[8:9], v[74:75] op_sel_hi:[0,1]
	v_and_b32_e32 v7, 0xffff0000, v1
	v_pk_mul_f32 v[4:5], v[4:5], v[6:7]
	v_lshlrev_b32_e32 v6, 16, v2
	v_cvt_pk_bf16_f32 v1, v4, v5
	v_pk_mul_f32 v[4:5], v[8:9], v[76:77] op_sel_hi:[0,1]
	v_and_b32_e32 v7, 0xffff0000, v2
	v_pk_mul_f32 v[4:5], v[4:5], v[6:7]
	v_lshlrev_b32_e32 v6, 16, v3
	v_cvt_pk_bf16_f32 v2, v4, v5
	v_pk_mul_f32 v[4:5], v[8:9], v[78:79] op_sel_hi:[0,1]
	v_and_b32_e32 v7, 0xffff0000, v3
	v_pk_mul_f32 v[4:5], v[4:5], v[6:7]
	v_add_u32_e32 v6, s6, v200
	v_cvt_pk_bf16_f32 v3, v4, v5
	ds_write2_b64 v205, v[0:1], v[2:3] offset0:12 offset1:14
	s_waitcnt lgkmcnt(0)
	s_barrier
	ds_read_b128 v[0:3], v234
	v_ashrrev_i32_e32 v7, 31, v6
	v_lshl_add_u64 v[4:5], v[186:187], 0, s[90:91]
	v_lshlrev_b64 v[6:7], 11, v[6:7]
	v_lshl_add_u64 v[6:7], v[4:5], 0, v[6:7]
	s_waitcnt lgkmcnt(0)
	global_store_dwordx4 v[6:7], v[0:3], off
	ds_read_b128 v[0:3], v209
	v_add_u32_e32 v6, s6, v201
	v_ashrrev_i32_e32 v7, 31, v6
	v_lshlrev_b64 v[6:7], 11, v[6:7]
	v_lshl_add_u64 v[6:7], v[4:5], 0, v[6:7]
	s_waitcnt lgkmcnt(0)
	global_store_dwordx4 v[6:7], v[0:3], off
	ds_read_b128 v[0:3], v222
	v_add_u32_e32 v6, s6, v202
	v_ashrrev_i32_e32 v7, 31, v6
	v_lshlrev_b64 v[6:7], 11, v[6:7]
	v_lshl_add_u64 v[6:7], v[4:5], 0, v[6:7]
	s_waitcnt lgkmcnt(0)
	global_store_dwordx4 v[6:7], v[0:3], off
	ds_read_b128 v[0:3], v224
	v_add_u32_e32 v6, s6, v203
	v_ashrrev_i32_e32 v7, 31, v6
	v_lshlrev_b64 v[6:7], 11, v[6:7]
	v_lshl_add_u64 v[4:5], v[4:5], 0, v[6:7]
	s_waitcnt lgkmcnt(0)
	global_store_dwordx4 v[4:5], v[0:3], off
	s_cbranch_vccnz .LBB0_91
	.p2align 6

.LBB0_111:
	v_add_u32_e32 v22, 1, v22
	v_cvt_f32_i32_e32 v26, v22
	v_and_b32_e32 v23, 0xffff0000, v9
	v_lshlrev_b32_e32 v22, 16, v9
	v_and_b32_e32 v9, 0xffff0000, v8
	v_div_scale_f32 v27, s[2:3], v26, v26, 1.0
	v_rcp_f32_e32 v28, v27
	v_lshlrev_b32_e32 v8, 16, v8
	v_and_b32_e32 v25, 0xffff0000, v11
	v_lshlrev_b32_e32 v24, 16, v11
	v_fma_f32 v29, -v27, v28, 1.0
	v_fmac_f32_e32 v28, v29, v28
	v_div_scale_f32 v29, vcc, 1.0, v26, 1.0
	v_mul_f32_e32 v30, v29, v28
	v_fma_f32 v31, -v27, v30, v29
	v_fmac_f32_e32 v30, v31, v28
	v_fma_f32 v27, -v27, v30, v29
	v_div_fmas_f32 v27, v27, v28, v30
	v_div_fixup_f32 v26, v27, v26, 1.0
	v_pk_add_f32 v[28:29], v[110:111], v[8:9]
	v_and_b32_e32 v11, 0xffff0000, v10
	v_pk_fma_f32 v[8:9], v[26:27], v[28:29], v[8:9] op_sel_hi:[0,1,1] neg_lo:[0,0,1] neg_hi:[0,0,1]
	s_waitcnt vmcnt(0)
	v_pk_mul_f32 v[8:9], v[4:5], v[8:9]
	v_lshlrev_b32_e32 v10, 16, v10
	v_pk_mul_f32 v[8:9], v[16:17], v[8:9]
	v_pk_add_f32 v[16:17], v[36:37], v[22:23]
	v_ashrrev_i32_e32 v141, 31, v140
	v_pk_fma_f32 v[16:17], v[26:27], v[16:17], v[22:23] op_sel_hi:[0,1,1] neg_lo:[0,0,1] neg_hi:[0,0,1]
	v_pk_mul_f32 v[16:17], v[6:7], v[16:17]
	v_cvt_pk_bf16_f32 v8, v8, v9
	v_pk_mul_f32 v[12:13], v[12:13], v[16:17]
	v_pk_add_f32 v[16:17], v[44:45], v[10:11]
	v_cvt_pk_bf16_f32 v9, v12, v13
	v_pk_fma_f32 v[10:11], v[26:27], v[16:17], v[10:11] op_sel_hi:[0,1,1] neg_lo:[0,0,1] neg_hi:[0,0,1]
	v_pk_add_f32 v[16:17], v[18:19], v[24:25]
	v_pk_mul_f32 v[10:11], v[0:1], v[10:11]
	v_pk_fma_f32 v[16:17], v[26:27], v[16:17], v[24:25] op_sel_hi:[0,1,1] neg_lo:[0,0,1] neg_hi:[0,0,1]
	v_pk_mul_f32 v[16:17], v[2:3], v[16:17]
	v_lshl_add_u64 v[12:13], s[28:29], 0, v[140:141]
	v_pk_mul_f32 v[10:11], v[20:21], v[10:11]
	v_pk_mul_f32 v[14:15], v[14:15], v[16:17]
	v_lshlrev_b64 v[12:13], 11, v[12:13]
	s_add_i32 s18, s18, s25
	s_sub_i32 s5, s5, s25
	v_cvt_pk_bf16_f32 v10, v10, v11
	v_cvt_pk_bf16_f32 v11, v14, v15
	v_lshl_add_u64 v[12:13], v[138:139], 0, v[12:13]
	s_cmpk_gt_i32 s18, 0x7ff
	global_store_dwordx4 v[12:13], v[8:11], off
	s_cbranch_scc1 .LBB0_238
	.p2align 6
